# SWIGLU epilogue: stores issued from a row-major lane mapping (4 consecutive lanes per row) via ds_bpermute
# baseline (speedup 1.0000x reference)
; DI unsigned pk2(float lo, float hi) { const f32x2v v = {lo, hi}; const bf16x2v b = __builtin_convertvector(v, bf16x2v); return __builtin_bit_cast(unsigned, b); }
; DI float siluf_(float x) { return x * sigmoidf_(x); }
; DI float rs_of(float ss, float inv_n) { return __builtin_amdgcn_rsqf(ss * inv_n + EPS); }
; DI float sum16_fq(const float* p, int fq) { const f32x4 a = *(const f32x4*)(p + 4 * fq); float s = (a[0] + a[1]) + (a[2] + a[3]); s += __shfl_xor(s, 16); s += __shfl_xor(s, 32); return s; }
; DI void epilogue(int kind, int l, const f32x4 (&acc)[2][2][4][2], const Unit& u, int wr, int wc, int fr, int fq) {
;     ...
;     if (E.mode == EM_SWIGLU) {
; #pragma unroll
;         for (int ai = 0; ai < 2; ++ai)
; #pragma unroll
;             for (int m = 0; m < 4; ++m) { const int row = row0 + ai * HALF + m * 16; const float rs = rs_of(sum16_fq(E.ss_in + (size_t)row * 16, fq), 1.f / 1024.f);
; #pragma unroll
;                 for (int bj = 0; bj < 2; ++bj) { const f32x4 g = acc[ai][bj][m][0] * rs, up = acc[ai][bj][m][1] * rs;
;                     u32x2 w; w.x = pk2(siluf_(g[0]) * up[0], siluf_(g[1]) * up[1]); w.y = pk2(siluf_(g[2]) * up[2], siluf_(g[3]) * up[3]);
;                     *(u32x2*)(E.o0 + (size_t)row * FF + ((col0 + bj * HALF) >> 1)) = w; } }
.LBB0_812:
	v_lshlrev_b32_e32 v24, 2, v166
	s_waitcnt lgkmcnt(0)
	v_lshl_add_u64 v[250:251], s[88:89], 0, v[24:25]
	v_ashrrev_i32_e32 v173, 31, v172
	v_lshlrev_b64 v[130:131], 6, v[172:173]
	v_lshl_add_u64 v[250:251], v[250:251], 0, v[130:131]
	v_mov_b32_e32 v252, 0x2000
	v_mov_b32_e32 v253, 0
	v_lshl_add_u64 v[252:253], v[250:251], 0, v[252:253]
	global_load_dwordx4 v[216:219], v[250:251], off
	global_load_dwordx4 v[220:223], v[250:251], off offset:1024
	global_load_dwordx4 v[224:227], v[250:251], off offset:2048
	global_load_dwordx4 v[228:231], v[250:251], off offset:3072
	global_load_dwordx4 v[232:235], v[252:253], off
	global_load_dwordx4 v[236:239], v[252:253], off offset:1024
	global_load_dwordx4 v[240:243], v[252:253], off offset:2048
	global_load_dwordx4 v[244:247], v[252:253], off offset:3072
	v_xor_b32_e32 v248, 16, v187
	v_xor_b32_e32 v249, 32, v187
	v_lshlrev_b32_e32 v248, 2, v248
	v_lshlrev_b32_e32 v249, 2, v249
	s_movk_i32 s6, 0x1600
	v_mov_b64_e32 v[130:131], s[78:79]
	v_mad_i64_i32 v[150:151], s[4:5], v172, s6, v[130:131]
	v_lshrrev_b32_e32 v132, 2, v187
	v_and_b32_e32 v133, 3, v187
	v_and_b32_e32 v24, 1, v133
	v_lshrrev_b32_e32 v134, 1, v133
	v_lshl_add_u32 v24, v24, 1, v134
	v_lshl_add_u32 v24, v24, 4, v132
	v_lshlrev_b32_e32 v152, 2, v24
	v_and_b32_e32 v24, 1, v133
	v_lshlrev_b32_e32 v24, 4, v24
	v_lshl_add_u32 v24, v134, 7, v24
	v_and_b32_e32 v134, 15, v187
	v_sub_u32_e32 v134, v132, v134
	v_mul_i32_i24_e32 v134, 0x1600, v134
	v_lshrrev_b32_e32 v135, 4, v187
	v_lshlrev_b32_e32 v135, 3, v135
	v_sub_u32_e32 v132, v174, v135
	v_add3_u32 v132, v132, v24, v134
	v_ashrrev_i32_e32 v133, 31, v132
	v_lshl_add_u64 v[150:151], v[132:133], 0, v[150:151]
	s_waitcnt vmcnt(0)
	v_add_f32_e32 v216, v217, v216
	v_add_f32_e32 v220, v221, v220
	v_add_f32_e32 v224, v225, v224
	v_add_f32_e32 v228, v229, v228
	v_add_f32_e32 v232, v233, v232
	v_add_f32_e32 v236, v237, v236
	v_add_f32_e32 v240, v241, v240
	v_add_f32_e32 v244, v245, v244
	v_add_f32_e32 v218, v218, v219
	v_add_f32_e32 v222, v222, v223
	v_add_f32_e32 v226, v226, v227
	v_add_f32_e32 v230, v230, v231
	v_add_f32_e32 v234, v234, v235
	v_add_f32_e32 v238, v238, v239
	v_add_f32_e32 v242, v242, v243
	v_add_f32_e32 v246, v246, v247
	v_add_f32_e32 v216, v216, v218
	v_add_f32_e32 v220, v220, v222
	v_add_f32_e32 v224, v224, v226
	v_add_f32_e32 v228, v228, v230
	v_add_f32_e32 v232, v232, v234
	v_add_f32_e32 v236, v236, v238
	v_add_f32_e32 v240, v240, v242
	v_add_f32_e32 v244, v244, v246
	ds_bpermute_b32 v217, v248, v216
	ds_bpermute_b32 v221, v248, v220
	ds_bpermute_b32 v225, v248, v224
	ds_bpermute_b32 v229, v248, v228
	ds_bpermute_b32 v233, v248, v232
	ds_bpermute_b32 v237, v248, v236
	ds_bpermute_b32 v241, v248, v240
	ds_bpermute_b32 v245, v248, v244
	s_waitcnt lgkmcnt(0)
	v_add_f32_e32 v216, v216, v217
	v_add_f32_e32 v220, v220, v221
	v_add_f32_e32 v224, v224, v225
	v_add_f32_e32 v228, v228, v229
	v_add_f32_e32 v232, v232, v233
	v_add_f32_e32 v236, v236, v237
	v_add_f32_e32 v240, v240, v241
	v_add_f32_e32 v244, v244, v245
	ds_bpermute_b32 v217, v249, v216
	ds_bpermute_b32 v221, v249, v220
	ds_bpermute_b32 v225, v249, v224
	ds_bpermute_b32 v229, v249, v228
	ds_bpermute_b32 v233, v249, v232
	ds_bpermute_b32 v237, v249, v236
	ds_bpermute_b32 v241, v249, v240
	ds_bpermute_b32 v245, v249, v244
	s_waitcnt lgkmcnt(0)
	v_add_f32_e32 v216, v216, v217
	v_add_f32_e32 v220, v220, v221
	v_add_f32_e32 v224, v224, v225
	v_add_f32_e32 v228, v228, v229
	v_add_f32_e32 v232, v232, v233
	v_add_f32_e32 v236, v236, v237
	v_add_f32_e32 v240, v240, v241
	v_add_f32_e32 v244, v244, v245
	v_fmamk_f32 v216, v216, 0x3a800000, v185
	v_fmamk_f32 v220, v220, 0x3a800000, v185
	v_fmamk_f32 v224, v224, 0x3a800000, v185
	v_fmamk_f32 v228, v228, 0x3a800000, v185
	v_fmamk_f32 v232, v232, 0x3a800000, v185
	v_fmamk_f32 v236, v236, 0x3a800000, v185
	v_fmamk_f32 v240, v240, 0x3a800000, v185
	v_fmamk_f32 v244, v244, 0x3a800000, v185
	v_rsq_f32_e32 v216, v216
	v_rsq_f32_e32 v220, v220
	v_rsq_f32_e32 v224, v224
	v_rsq_f32_e32 v228, v228
	v_rsq_f32_e32 v232, v232
	v_rsq_f32_e32 v236, v236
	v_rsq_f32_e32 v240, v240
	v_rsq_f32_e32 v244, v244
	v_mul_f32_e32 v217, 0xbfb8aa3b, v216
	v_mul_f32_e32 v221, 0xbfb8aa3b, v220
	v_mul_f32_e32 v225, 0xbfb8aa3b, v224
	v_mul_f32_e32 v229, 0xbfb8aa3b, v228
	v_mul_f32_e32 v233, 0xbfb8aa3b, v232
	v_mul_f32_e32 v237, 0xbfb8aa3b, v236
	v_mul_f32_e32 v241, 0xbfb8aa3b, v240
	v_mul_f32_e32 v245, 0xbfb8aa3b, v244
	v_mul_f32_e32 v218, v216, v216
	v_mul_f32_e32 v222, v220, v220
	v_mul_f32_e32 v226, v224, v224
	v_mul_f32_e32 v230, v228, v228
	v_mul_f32_e32 v234, v232, v232
	v_mul_f32_e32 v238, v236, v236
	v_mul_f32_e32 v242, v240, v240
	v_mul_f32_e32 v246, v244, v244
	v_mul_f32_e32 v130, v126, v217
	v_mul_f32_e32 v131, v127, v217
	v_mul_f32_e32 v132, v128, v217
	v_mul_f32_e32 v133, v129, v217
	v_exp_f32_e32 v130, v130
	v_exp_f32_e32 v131, v131
	v_exp_f32_e32 v132, v132
	v_exp_f32_e32 v133, v133
	v_pk_mul_f32 v[134:135], v[126:127], v[122:123]
	v_pk_mul_f32 v[136:137], v[128:129], v[124:125]
	v_add_f32_e32 v130, 1.0, v130
	v_add_f32_e32 v131, 1.0, v131
	v_add_f32_e32 v132, 1.0, v132
	v_add_f32_e32 v133, 1.0, v133
	v_rcp_f32_e32 v130, v130
	v_rcp_f32_e32 v131, v131
	v_rcp_f32_e32 v132, v132
	v_rcp_f32_e32 v133, v133
	v_pk_mul_f32 v[130:131], v[130:131], v[218:219] op_sel_hi:[1,0]
	v_pk_mul_f32 v[132:133], v[132:133], v[218:219] op_sel_hi:[1,0]
	v_pk_mul_f32 v[134:135], v[134:135], v[130:131]
	v_pk_mul_f32 v[136:137], v[136:137], v[132:133]
	v_cvt_pk_bf16_f32 v138, v134, v135
	v_cvt_pk_bf16_f32 v139, v136, v137
	v_mul_f32_e32 v130, v118, v217
	v_mul_f32_e32 v131, v119, v217
	v_mul_f32_e32 v132, v120, v217
	v_mul_f32_e32 v133, v121, v217
	v_exp_f32_e32 v130, v130
	v_exp_f32_e32 v131, v131
	v_exp_f32_e32 v132, v132
	v_exp_f32_e32 v133, v133
	v_pk_mul_f32 v[134:135], v[118:119], v[114:115]
	v_pk_mul_f32 v[136:137], v[120:121], v[116:117]
	v_add_f32_e32 v130, 1.0, v130
	v_add_f32_e32 v131, 1.0, v131
	v_add_f32_e32 v132, 1.0, v132
	v_add_f32_e32 v133, 1.0, v133
	v_rcp_f32_e32 v130, v130
	v_rcp_f32_e32 v131, v131
	v_rcp_f32_e32 v132, v132
	v_rcp_f32_e32 v133, v133
	v_pk_mul_f32 v[130:131], v[130:131], v[218:219] op_sel_hi:[1,0]
	v_pk_mul_f32 v[132:133], v[132:133], v[218:219] op_sel_hi:[1,0]
	v_pk_mul_f32 v[134:135], v[134:135], v[130:131]
	v_pk_mul_f32 v[136:137], v[136:137], v[132:133]
	v_cvt_pk_bf16_f32 v140, v134, v135
	v_cvt_pk_bf16_f32 v141, v136, v137
	s_nop 1
	v_permlane16_swap_b32_e32 v138, v140
	v_permlane16_swap_b32_e32 v139, v141
	ds_bpermute_b32 v138, v152, v138
	ds_bpermute_b32 v139, v152, v139
	ds_bpermute_b32 v140, v152, v140
	ds_bpermute_b32 v141, v152, v141
	s_waitcnt lgkmcnt(0)
; DI unsigned pk2(float lo, float hi) { const f32x2v v = {lo, hi}; const bf16x2v b = __builtin_convertvector(v, bf16x2v); return __builtin_bit_cast(unsigned, b); }
; DI float siluf_(float x) { return x * sigmoidf_(x); }
; DI float rs_of(float ss, float inv_n) { return __builtin_amdgcn_rsqf(ss * inv_n + EPS); }
; DI float sum16_fq(const float* p, int fq) { const f32x4 a = *(const f32x4*)(p + 4 * fq); float s = (a[0] + a[1]) + (a[2] + a[3]); s += __shfl_xor(s, 16); s += __shfl_xor(s, 32); return s; }
; DI void epilogue(int kind, int l, const f32x4 (&acc)[2][2][4][2], const Unit& u, int wr, int wc, int fr, int fq) {
;     ...
;             for (int m = 0; m < 4; ++m) { const int row = row0 + ai * HALF + m * 16; const float rs = rs_of(sum16_fq(E.ss_in + (size_t)row * 16, fq), 1.f / 1024.f);
; #pragma unroll
;                 for (int bj = 0; bj < 2; ++bj) { const f32x4 g = acc[ai][bj][m][0] * rs, up = acc[ai][bj][m][1] * rs;
;                     u32x2 w; w.x = pk2(siluf_(g[0]) * up[0], siluf_(g[1]) * up[1]); w.y = pk2(siluf_(g[2]) * up[2], siluf_(g[3]) * up[3]);
;                     *(u32x2*)(E.o0 + (size_t)row * FF + ((col0 + bj * HALF) >> 1)) = w; } }
	global_store_dwordx4 v[150:151], v[138:141], off
	v_add_co_u32_e32 v150, vcc, 0x16000, v150
	s_nop 1
	v_addc_co_u32_e32 v151, vcc, 0, v151, vcc
	v_mul_f32_e32 v130, v110, v221
	v_mul_f32_e32 v131, v111, v221
	v_mul_f32_e32 v132, v112, v221
	v_mul_f32_e32 v133, v113, v221
	v_exp_f32_e32 v130, v130
	v_exp_f32_e32 v131, v131
	v_exp_f32_e32 v132, v132
	v_exp_f32_e32 v133, v133
	v_pk_mul_f32 v[134:135], v[110:111], v[106:107]
	v_pk_mul_f32 v[136:137], v[112:113], v[108:109]
	v_add_f32_e32 v130, 1.0, v130
	v_add_f32_e32 v131, 1.0, v131
	v_add_f32_e32 v132, 1.0, v132
	v_add_f32_e32 v133, 1.0, v133
	v_rcp_f32_e32 v130, v130
	v_rcp_f32_e32 v131, v131
	v_rcp_f32_e32 v132, v132
	v_rcp_f32_e32 v133, v133
	v_pk_mul_f32 v[130:131], v[130:131], v[222:223] op_sel_hi:[1,0]
	v_pk_mul_f32 v[132:133], v[132:133], v[222:223] op_sel_hi:[1,0]
	v_pk_mul_f32 v[134:135], v[134:135], v[130:131]
	v_pk_mul_f32 v[136:137], v[136:137], v[132:133]
	v_cvt_pk_bf16_f32 v142, v134, v135
	v_cvt_pk_bf16_f32 v143, v136, v137
	v_mul_f32_e32 v130, v102, v221
	v_mul_f32_e32 v131, v103, v221
	v_mul_f32_e32 v132, v104, v221
	v_mul_f32_e32 v133, v105, v221
	v_exp_f32_e32 v130, v130
	v_exp_f32_e32 v131, v131
	v_exp_f32_e32 v132, v132
	v_exp_f32_e32 v133, v133
	v_pk_mul_f32 v[134:135], v[102:103], v[98:99]
	v_pk_mul_f32 v[136:137], v[104:105], v[100:101]
	v_add_f32_e32 v130, 1.0, v130
	v_add_f32_e32 v131, 1.0, v131
	v_add_f32_e32 v132, 1.0, v132
	v_add_f32_e32 v133, 1.0, v133
	v_rcp_f32_e32 v130, v130
	v_rcp_f32_e32 v131, v131
	v_rcp_f32_e32 v132, v132
	v_rcp_f32_e32 v133, v133
	v_pk_mul_f32 v[130:131], v[130:131], v[222:223] op_sel_hi:[1,0]
	v_pk_mul_f32 v[132:133], v[132:133], v[222:223] op_sel_hi:[1,0]
	v_pk_mul_f32 v[134:135], v[134:135], v[130:131]
	v_pk_mul_f32 v[136:137], v[136:137], v[132:133]
	v_cvt_pk_bf16_f32 v144, v134, v135
	v_cvt_pk_bf16_f32 v145, v136, v137
	s_nop 1
	v_permlane16_swap_b32_e32 v142, v144
	v_permlane16_swap_b32_e32 v143, v145
	ds_bpermute_b32 v142, v152, v142
	ds_bpermute_b32 v143, v152, v143
	ds_bpermute_b32 v144, v152, v144
	ds_bpermute_b32 v145, v152, v145
	s_waitcnt lgkmcnt(0)
	global_store_dwordx4 v[150:151], v[142:145], off
	v_add_co_u32_e32 v150, vcc, 0x16000, v150
	s_nop 1
	v_addc_co_u32_e32 v151, vcc, 0, v151, vcc
	v_mul_f32_e32 v130, v94, v225
	v_mul_f32_e32 v131, v95, v225
	v_mul_f32_e32 v132, v96, v225
	v_mul_f32_e32 v133, v97, v225
	v_exp_f32_e32 v130, v130
	v_exp_f32_e32 v131, v131
	v_exp_f32_e32 v132, v132
	v_exp_f32_e32 v133, v133
	v_pk_mul_f32 v[134:135], v[94:95], v[90:91]
	v_pk_mul_f32 v[136:137], v[96:97], v[92:93]
	v_add_f32_e32 v130, 1.0, v130
	v_add_f32_e32 v131, 1.0, v131
	v_add_f32_e32 v132, 1.0, v132
	v_add_f32_e32 v133, 1.0, v133
	v_rcp_f32_e32 v130, v130
	v_rcp_f32_e32 v131, v131
	v_rcp_f32_e32 v132, v132
	v_rcp_f32_e32 v133, v133
	v_pk_mul_f32 v[130:131], v[130:131], v[226:227] op_sel_hi:[1,0]
	v_pk_mul_f32 v[132:133], v[132:133], v[226:227] op_sel_hi:[1,0]
	v_pk_mul_f32 v[134:135], v[134:135], v[130:131]
	v_pk_mul_f32 v[136:137], v[136:137], v[132:133]
	v_cvt_pk_bf16_f32 v138, v134, v135
	v_cvt_pk_bf16_f32 v139, v136, v137
	v_mul_f32_e32 v130, v86, v225
	v_mul_f32_e32 v131, v87, v225
	v_mul_f32_e32 v132, v88, v225
	v_mul_f32_e32 v133, v89, v225
	v_exp_f32_e32 v130, v130
	v_exp_f32_e32 v131, v131
	v_exp_f32_e32 v132, v132
	v_exp_f32_e32 v133, v133
	v_pk_mul_f32 v[134:135], v[86:87], v[82:83]
	v_pk_mul_f32 v[136:137], v[88:89], v[84:85]
	v_add_f32_e32 v130, 1.0, v130
	v_add_f32_e32 v131, 1.0, v131
	v_add_f32_e32 v132, 1.0, v132
	v_add_f32_e32 v133, 1.0, v133
	v_rcp_f32_e32 v130, v130
	v_rcp_f32_e32 v131, v131
	v_rcp_f32_e32 v132, v132
	v_rcp_f32_e32 v133, v133
	v_pk_mul_f32 v[130:131], v[130:131], v[226:227] op_sel_hi:[1,0]
	v_pk_mul_f32 v[132:133], v[132:133], v[226:227] op_sel_hi:[1,0]
	v_pk_mul_f32 v[134:135], v[134:135], v[130:131]
	v_pk_mul_f32 v[136:137], v[136:137], v[132:133]
	v_cvt_pk_bf16_f32 v140, v134, v135
	v_cvt_pk_bf16_f32 v141, v136, v137
	s_nop 1
	v_permlane16_swap_b32_e32 v138, v140
	v_permlane16_swap_b32_e32 v139, v141
	ds_bpermute_b32 v138, v152, v138
	ds_bpermute_b32 v139, v152, v139
	ds_bpermute_b32 v140, v152, v140
	ds_bpermute_b32 v141, v152, v141
	s_waitcnt lgkmcnt(0)
	global_store_dwordx4 v[150:151], v[138:141], off
	v_add_co_u32_e32 v150, vcc, 0x16000, v150
	s_nop 1
	v_addc_co_u32_e32 v151, vcc, 0, v151, vcc
	v_mul_f32_e32 v130, v78, v229
	v_mul_f32_e32 v131, v79, v229
	v_mul_f32_e32 v132, v80, v229
	v_mul_f32_e32 v133, v81, v229
	v_exp_f32_e32 v130, v130
	v_exp_f32_e32 v131, v131
	v_exp_f32_e32 v132, v132
	v_exp_f32_e32 v133, v133
	v_pk_mul_f32 v[134:135], v[78:79], v[74:75]
	v_pk_mul_f32 v[136:137], v[80:81], v[76:77]
	v_add_f32_e32 v130, 1.0, v130
	v_add_f32_e32 v131, 1.0, v131
	v_add_f32_e32 v132, 1.0, v132
	v_add_f32_e32 v133, 1.0, v133
	v_rcp_f32_e32 v130, v130
	v_rcp_f32_e32 v131, v131
	v_rcp_f32_e32 v132, v132
	v_rcp_f32_e32 v133, v133
	v_pk_mul_f32 v[130:131], v[130:131], v[230:231] op_sel_hi:[1,0]
	v_pk_mul_f32 v[132:133], v[132:133], v[230:231] op_sel_hi:[1,0]
	v_pk_mul_f32 v[134:135], v[134:135], v[130:131]
	v_pk_mul_f32 v[136:137], v[136:137], v[132:133]
	v_cvt_pk_bf16_f32 v142, v134, v135
	v_cvt_pk_bf16_f32 v143, v136, v137
	v_mul_f32_e32 v130, v70, v229
	v_mul_f32_e32 v131, v71, v229
	v_mul_f32_e32 v132, v72, v229
	v_mul_f32_e32 v133, v73, v229
	v_exp_f32_e32 v130, v130
	v_exp_f32_e32 v131, v131
	v_exp_f32_e32 v132, v132
	v_exp_f32_e32 v133, v133
	v_pk_mul_f32 v[134:135], v[70:71], v[66:67]
	v_pk_mul_f32 v[136:137], v[72:73], v[68:69]
	v_add_f32_e32 v130, 1.0, v130
	v_add_f32_e32 v131, 1.0, v131
	v_add_f32_e32 v132, 1.0, v132
	v_add_f32_e32 v133, 1.0, v133
	v_rcp_f32_e32 v130, v130
	v_rcp_f32_e32 v131, v131
	v_rcp_f32_e32 v132, v132
	v_rcp_f32_e32 v133, v133
	v_pk_mul_f32 v[130:131], v[130:131], v[230:231] op_sel_hi:[1,0]
	v_pk_mul_f32 v[132:133], v[132:133], v[230:231] op_sel_hi:[1,0]
	v_pk_mul_f32 v[134:135], v[134:135], v[130:131]
	v_pk_mul_f32 v[136:137], v[136:137], v[132:133]
	v_cvt_pk_bf16_f32 v144, v134, v135
	v_cvt_pk_bf16_f32 v145, v136, v137
	s_nop 1
	v_permlane16_swap_b32_e32 v142, v144
	v_permlane16_swap_b32_e32 v143, v145
	ds_bpermute_b32 v142, v152, v142
	ds_bpermute_b32 v143, v152, v143
	ds_bpermute_b32 v144, v152, v144
	ds_bpermute_b32 v145, v152, v145
	s_waitcnt lgkmcnt(0)
; DI unsigned pk2(float lo, float hi) { const f32x2v v = {lo, hi}; const bf16x2v b = __builtin_convertvector(v, bf16x2v); return __builtin_bit_cast(unsigned, b); }
; DI float siluf_(float x) { return x * sigmoidf_(x); }
; DI float rs_of(float ss, float inv_n) { return __builtin_amdgcn_rsqf(ss * inv_n + EPS); }
; DI float sum16_fq(const float* p, int fq) { const f32x4 a = *(const f32x4*)(p + 4 * fq); float s = (a[0] + a[1]) + (a[2] + a[3]); s += __shfl_xor(s, 16); s += __shfl_xor(s, 32); return s; }
; DI void epilogue(int kind, int l, const f32x4 (&acc)[2][2][4][2], const Unit& u, int wr, int wc, int fr, int fq) {
;     ...
;             for (int m = 0; m < 4; ++m) { const int row = row0 + ai * HALF + m * 16; const float rs = rs_of(sum16_fq(E.ss_in + (size_t)row * 16, fq), 1.f / 1024.f);
; #pragma unroll
;                 for (int bj = 0; bj < 2; ++bj) { const f32x4 g = acc[ai][bj][m][0] * rs, up = acc[ai][bj][m][1] * rs;
;                     u32x2 w; w.x = pk2(siluf_(g[0]) * up[0], siluf_(g[1]) * up[1]); w.y = pk2(siluf_(g[2]) * up[2], siluf_(g[3]) * up[3]);
;                     *(u32x2*)(E.o0 + (size_t)row * FF + ((col0 + bj * HALF) >> 1)) = w; } }
	global_store_dwordx4 v[150:151], v[142:145], off
	v_add_co_u32_e32 v150, vcc, 0x6e000, v150
	s_nop 1
	v_addc_co_u32_e32 v151, vcc, 0, v151, vcc
	v_mul_f32_e32 v130, v62, v233
	v_mul_f32_e32 v131, v63, v233
	v_mul_f32_e32 v132, v64, v233
	v_mul_f32_e32 v133, v65, v233
	v_exp_f32_e32 v130, v130
	v_exp_f32_e32 v131, v131
	v_exp_f32_e32 v132, v132
	v_exp_f32_e32 v133, v133
	v_pk_mul_f32 v[134:135], v[62:63], v[58:59]
	v_pk_mul_f32 v[136:137], v[64:65], v[60:61]
	v_add_f32_e32 v130, 1.0, v130
	v_add_f32_e32 v131, 1.0, v131
	v_add_f32_e32 v132, 1.0, v132
	v_add_f32_e32 v133, 1.0, v133
	v_rcp_f32_e32 v130, v130
	v_rcp_f32_e32 v131, v131
	v_rcp_f32_e32 v132, v132
	v_rcp_f32_e32 v133, v133
	v_pk_mul_f32 v[130:131], v[130:131], v[234:235] op_sel_hi:[1,0]
	v_pk_mul_f32 v[132:133], v[132:133], v[234:235] op_sel_hi:[1,0]
	v_pk_mul_f32 v[134:135], v[134:135], v[130:131]
	v_pk_mul_f32 v[136:137], v[136:137], v[132:133]
	v_cvt_pk_bf16_f32 v138, v134, v135
	v_cvt_pk_bf16_f32 v139, v136, v137
	v_mul_f32_e32 v130, v54, v233
	v_mul_f32_e32 v131, v55, v233
	v_mul_f32_e32 v132, v56, v233
	v_mul_f32_e32 v133, v57, v233
	v_exp_f32_e32 v130, v130
	v_exp_f32_e32 v131, v131
	v_exp_f32_e32 v132, v132
	v_exp_f32_e32 v133, v133
	v_pk_mul_f32 v[134:135], v[54:55], v[50:51]
	v_pk_mul_f32 v[136:137], v[56:57], v[52:53]
	v_add_f32_e32 v130, 1.0, v130
	v_add_f32_e32 v131, 1.0, v131
	v_add_f32_e32 v132, 1.0, v132
	v_add_f32_e32 v133, 1.0, v133
	v_rcp_f32_e32 v130, v130
	v_rcp_f32_e32 v131, v131
	v_rcp_f32_e32 v132, v132
	v_rcp_f32_e32 v133, v133
	v_pk_mul_f32 v[130:131], v[130:131], v[234:235] op_sel_hi:[1,0]
	v_pk_mul_f32 v[132:133], v[132:133], v[234:235] op_sel_hi:[1,0]
	v_pk_mul_f32 v[134:135], v[134:135], v[130:131]
	v_pk_mul_f32 v[136:137], v[136:137], v[132:133]
	v_cvt_pk_bf16_f32 v140, v134, v135
	v_cvt_pk_bf16_f32 v141, v136, v137
	s_nop 1
	v_permlane16_swap_b32_e32 v138, v140
	v_permlane16_swap_b32_e32 v139, v141
	ds_bpermute_b32 v138, v152, v138
	ds_bpermute_b32 v139, v152, v139
	ds_bpermute_b32 v140, v152, v140
	ds_bpermute_b32 v141, v152, v141
	s_waitcnt lgkmcnt(0)
	global_store_dwordx4 v[150:151], v[138:141], off
	v_add_co_u32_e32 v150, vcc, 0x16000, v150
	s_nop 1
	v_addc_co_u32_e32 v151, vcc, 0, v151, vcc
	v_mul_f32_e32 v130, v46, v237
	v_mul_f32_e32 v131, v47, v237
	v_mul_f32_e32 v132, v48, v237
	v_mul_f32_e32 v133, v49, v237
	v_exp_f32_e32 v130, v130
	v_exp_f32_e32 v131, v131
	v_exp_f32_e32 v132, v132
	v_exp_f32_e32 v133, v133
	v_pk_mul_f32 v[134:135], v[46:47], v[42:43]
	v_pk_mul_f32 v[136:137], v[48:49], v[44:45]
	v_add_f32_e32 v130, 1.0, v130
	v_add_f32_e32 v131, 1.0, v131
	v_add_f32_e32 v132, 1.0, v132
	v_add_f32_e32 v133, 1.0, v133
	v_rcp_f32_e32 v130, v130
	v_rcp_f32_e32 v131, v131
	v_rcp_f32_e32 v132, v132
	v_rcp_f32_e32 v133, v133
	v_pk_mul_f32 v[130:131], v[130:131], v[238:239] op_sel_hi:[1,0]
	v_pk_mul_f32 v[132:133], v[132:133], v[238:239] op_sel_hi:[1,0]
	v_pk_mul_f32 v[134:135], v[134:135], v[130:131]
	v_pk_mul_f32 v[136:137], v[136:137], v[132:133]
	v_cvt_pk_bf16_f32 v142, v134, v135
	v_cvt_pk_bf16_f32 v143, v136, v137
	v_mul_f32_e32 v130, v38, v237
	v_mul_f32_e32 v131, v39, v237
	v_mul_f32_e32 v132, v40, v237
	v_mul_f32_e32 v133, v41, v237
	v_exp_f32_e32 v130, v130
	v_exp_f32_e32 v131, v131
	v_exp_f32_e32 v132, v132
	v_exp_f32_e32 v133, v133
	v_pk_mul_f32 v[134:135], v[38:39], v[34:35]
	v_pk_mul_f32 v[136:137], v[40:41], v[36:37]
	v_add_f32_e32 v130, 1.0, v130
	v_add_f32_e32 v131, 1.0, v131
	v_add_f32_e32 v132, 1.0, v132
	v_add_f32_e32 v133, 1.0, v133
	v_rcp_f32_e32 v130, v130
	v_rcp_f32_e32 v131, v131
	v_rcp_f32_e32 v132, v132
	v_rcp_f32_e32 v133, v133
	v_pk_mul_f32 v[130:131], v[130:131], v[238:239] op_sel_hi:[1,0]
	v_pk_mul_f32 v[132:133], v[132:133], v[238:239] op_sel_hi:[1,0]
	v_pk_mul_f32 v[134:135], v[134:135], v[130:131]
	v_pk_mul_f32 v[136:137], v[136:137], v[132:133]
	v_cvt_pk_bf16_f32 v144, v134, v135
	v_cvt_pk_bf16_f32 v145, v136, v137
	s_nop 1
	v_permlane16_swap_b32_e32 v142, v144
	v_permlane16_swap_b32_e32 v143, v145
	ds_bpermute_b32 v142, v152, v142
	ds_bpermute_b32 v143, v152, v143
	ds_bpermute_b32 v144, v152, v144
	ds_bpermute_b32 v145, v152, v145
	s_waitcnt lgkmcnt(0)
; DI unsigned pk2(float lo, float hi) { const f32x2v v = {lo, hi}; const bf16x2v b = __builtin_convertvector(v, bf16x2v); return __builtin_bit_cast(unsigned, b); }
; DI float siluf_(float x) { return x * sigmoidf_(x); }
; DI float rs_of(float ss, float inv_n) { return __builtin_amdgcn_rsqf(ss * inv_n + EPS); }
; DI float sum16_fq(const float* p, int fq) { const f32x4 a = *(const f32x4*)(p + 4 * fq); float s = (a[0] + a[1]) + (a[2] + a[3]); s += __shfl_xor(s, 16); s += __shfl_xor(s, 32); return s; }
; DI void epilogue(int kind, int l, const f32x4 (&acc)[2][2][4][2], const Unit& u, int wr, int wc, int fr, int fq) {
;     ...
;             for (int m = 0; m < 4; ++m) { const int row = row0 + ai * HALF + m * 16; const float rs = rs_of(sum16_fq(E.ss_in + (size_t)row * 16, fq), 1.f / 1024.f);
; #pragma unroll
;                 for (int bj = 0; bj < 2; ++bj) { const f32x4 g = acc[ai][bj][m][0] * rs, up = acc[ai][bj][m][1] * rs;
;                     u32x2 w; w.x = pk2(siluf_(g[0]) * up[0], siluf_(g[1]) * up[1]); w.y = pk2(siluf_(g[2]) * up[2], siluf_(g[3]) * up[3]);
;                     *(u32x2*)(E.o0 + (size_t)row * FF + ((col0 + bj * HALF) >> 1)) = w; } }
	global_store_dwordx4 v[150:151], v[142:145], off
	v_add_co_u32_e32 v150, vcc, 0x16000, v150
	s_nop 1
	v_addc_co_u32_e32 v151, vcc, 0, v151, vcc
	v_mul_f32_e32 v130, v30, v241
	v_mul_f32_e32 v131, v31, v241
	v_mul_f32_e32 v132, v32, v241
	v_mul_f32_e32 v133, v33, v241
	v_exp_f32_e32 v130, v130
	v_exp_f32_e32 v131, v131
	v_exp_f32_e32 v132, v132
	v_exp_f32_e32 v133, v133
	v_pk_mul_f32 v[134:135], v[30:31], v[26:27]
	v_pk_mul_f32 v[136:137], v[32:33], v[28:29]
	v_add_f32_e32 v130, 1.0, v130
	v_add_f32_e32 v131, 1.0, v131
	v_add_f32_e32 v132, 1.0, v132
	v_add_f32_e32 v133, 1.0, v133
	v_rcp_f32_e32 v130, v130
	v_rcp_f32_e32 v131, v131
	v_rcp_f32_e32 v132, v132
	v_rcp_f32_e32 v133, v133
	v_pk_mul_f32 v[130:131], v[130:131], v[242:243] op_sel_hi:[1,0]
	v_pk_mul_f32 v[132:133], v[132:133], v[242:243] op_sel_hi:[1,0]
	v_pk_mul_f32 v[134:135], v[134:135], v[130:131]
	v_pk_mul_f32 v[136:137], v[136:137], v[132:133]
	v_cvt_pk_bf16_f32 v138, v134, v135
	v_cvt_pk_bf16_f32 v139, v136, v137
	v_mul_f32_e32 v130, v20, v241
	v_mul_f32_e32 v131, v21, v241
	v_mul_f32_e32 v132, v22, v241
	v_mul_f32_e32 v133, v23, v241
	v_exp_f32_e32 v130, v130
	v_exp_f32_e32 v131, v131
	v_exp_f32_e32 v132, v132
	v_exp_f32_e32 v133, v133
	v_pk_mul_f32 v[134:135], v[20:21], v[16:17]
	v_pk_mul_f32 v[136:137], v[22:23], v[18:19]
	v_add_f32_e32 v130, 1.0, v130
	v_add_f32_e32 v131, 1.0, v131
	v_add_f32_e32 v132, 1.0, v132
	v_add_f32_e32 v133, 1.0, v133
	v_rcp_f32_e32 v130, v130
	v_rcp_f32_e32 v131, v131
	v_rcp_f32_e32 v132, v132
	v_rcp_f32_e32 v133, v133
	v_pk_mul_f32 v[130:131], v[130:131], v[242:243] op_sel_hi:[1,0]
	v_pk_mul_f32 v[132:133], v[132:133], v[242:243] op_sel_hi:[1,0]
	v_pk_mul_f32 v[134:135], v[134:135], v[130:131]
	v_pk_mul_f32 v[136:137], v[136:137], v[132:133]
	v_cvt_pk_bf16_f32 v140, v134, v135
	v_cvt_pk_bf16_f32 v141, v136, v137
	s_nop 1
	v_permlane16_swap_b32_e32 v138, v140
	v_permlane16_swap_b32_e32 v139, v141
	ds_bpermute_b32 v138, v152, v138
	ds_bpermute_b32 v139, v152, v139
	ds_bpermute_b32 v140, v152, v140
	ds_bpermute_b32 v141, v152, v141
	s_waitcnt lgkmcnt(0)
	global_store_dwordx4 v[150:151], v[138:141], off
	v_add_co_u32_e32 v150, vcc, 0x16000, v150
	s_nop 1
	v_addc_co_u32_e32 v151, vcc, 0, v151, vcc
	v_mul_f32_e32 v130, v12, v245
	v_mul_f32_e32 v131, v13, v245
	v_mul_f32_e32 v132, v14, v245
	v_mul_f32_e32 v133, v15, v245
	v_exp_f32_e32 v130, v130
	v_exp_f32_e32 v131, v131
	v_exp_f32_e32 v132, v132
	v_exp_f32_e32 v133, v133
	v_pk_mul_f32 v[134:135], v[12:13], v[8:9]
	v_pk_mul_f32 v[136:137], v[14:15], v[10:11]
	v_add_f32_e32 v130, 1.0, v130
	v_add_f32_e32 v131, 1.0, v131
	v_add_f32_e32 v132, 1.0, v132
	v_add_f32_e32 v133, 1.0, v133
	v_rcp_f32_e32 v130, v130
	v_rcp_f32_e32 v131, v131
	v_rcp_f32_e32 v132, v132
	v_rcp_f32_e32 v133, v133
	v_pk_mul_f32 v[130:131], v[130:131], v[246:247] op_sel_hi:[1,0]
	v_pk_mul_f32 v[132:133], v[132:133], v[246:247] op_sel_hi:[1,0]
	v_pk_mul_f32 v[134:135], v[134:135], v[130:131]
	v_pk_mul_f32 v[136:137], v[136:137], v[132:133]
	v_cvt_pk_bf16_f32 v142, v134, v135
	v_cvt_pk_bf16_f32 v143, v136, v137
	v_mul_f32_e32 v130, v4, v245
	v_mul_f32_e32 v131, v5, v245
	v_mul_f32_e32 v132, v6, v245
	v_mul_f32_e32 v133, v7, v245
	v_exp_f32_e32 v130, v130
	v_exp_f32_e32 v131, v131
	v_exp_f32_e32 v132, v132
	v_exp_f32_e32 v133, v133
	v_pk_mul_f32 v[134:135], v[4:5], v[0:1]
	v_pk_mul_f32 v[136:137], v[6:7], v[2:3]
	v_add_f32_e32 v130, 1.0, v130
	v_add_f32_e32 v131, 1.0, v131
	v_add_f32_e32 v132, 1.0, v132
	v_add_f32_e32 v133, 1.0, v133
	v_rcp_f32_e32 v130, v130
	v_rcp_f32_e32 v131, v131
	v_rcp_f32_e32 v132, v132
	v_rcp_f32_e32 v133, v133
	v_pk_mul_f32 v[130:131], v[130:131], v[246:247] op_sel_hi:[1,0]
	v_pk_mul_f32 v[132:133], v[132:133], v[246:247] op_sel_hi:[1,0]
	v_pk_mul_f32 v[134:135], v[134:135], v[130:131]
	v_pk_mul_f32 v[136:137], v[136:137], v[132:133]
	v_cvt_pk_bf16_f32 v144, v134, v135
	v_cvt_pk_bf16_f32 v145, v136, v137
	s_nop 1
	v_permlane16_swap_b32_e32 v142, v144
	v_permlane16_swap_b32_e32 v143, v145
	ds_bpermute_b32 v142, v152, v142
	ds_bpermute_b32 v143, v152, v143
	ds_bpermute_b32 v144, v152, v144
	ds_bpermute_b32 v145, v152, v145
	s_waitcnt lgkmcnt(0)
	global_store_dwordx4 v[150:151], v[142:145], off
